# v15 + RG-LRU sample items: the three f32 conv-state row loads issued together into distinct registers, one wait, then converted (were load-wait-convert three times)
# baseline (speedup 1.0000x reference)
; __device__ __forceinline__ unsigned cvt_pk_bf16(float lo, float hi) { unsigned r; asm volatile("v_cvt_pk_bf16_f32 %0, %1, %2" : "=v"(r) : "v"(lo), "v"(hi)); return r; }
; __device__ __forceinline__ void lru_item(const Params& p, LAS unsigned char* L, int item, bool load_w) {
;     ...
;         if (cthr) {
;             if (pos >= 0) xr[r] = *(const u32x4*)(Z2 + (unsigned)((rbase + pos) * 3072u + chc));
;             else if (smp) {
;                 const float* hp = p.in[5] + ((size_t)b * 3 + (3 + pos)) * 1536 + chc;
;                 const f32x4 h0 = *(const f32x4*)hp, h1 = *(const f32x4*)(hp + 4);
;                 xr[r].x = cvt_pk_bf16(h0[0], h0[1]); xr[r].y = cvt_pk_bf16(h0[2], h0[3]); xr[r].z = cvt_pk_bf16(h1[0], h1[1]); xr[r].w = cvt_pk_bf16(h1[2], h1[3]);
;             }
.LBB0_1163:
	s_andn2_saveexec_b64 s[16:17], s[16:17]
	s_cbranch_execz .LBB0_1165
	v_readlane_b32 s48, v250, 4
	v_readlane_b32 s50, v250, 6
	v_readlane_b32 s51, v250, 7
	v_readlane_b32 s58, v250, 14
	v_readlane_b32 s59, v250, 15
	s_mul_i32 s26, s24, 0x1800
	s_mov_b64 s[50:51], s[58:59]
	s_mul_hi_u32 s23, s24, 0x1800
	s_add_u32 s26, s50, s26
	s_addc_u32 s27, s51, s23
	v_lshl_add_u64 v[4:5], v[60:61], 2, s[26:27]
	global_load_dwordx4 v[190:193], v[4:5], off
	s_nop 0
	global_load_dwordx4 v[194:197], v[4:5], off offset:16
	v_readlane_b32 s49, v250, 5
	v_readlane_b32 s52, v250, 8
	v_readlane_b32 s53, v250, 9
	v_readlane_b32 s54, v250, 10
	v_readlane_b32 s55, v250, 11
	v_readlane_b32 s56, v250, 12
	v_readlane_b32 s57, v250, 13
	v_readlane_b32 s60, v250, 16
	v_readlane_b32 s61, v250, 17
	v_readlane_b32 s62, v250, 18
	v_readlane_b32 s63, v250, 19

; __device__ __forceinline__ unsigned cvt_pk_bf16(float lo, float hi) { unsigned r; asm volatile("v_cvt_pk_bf16_f32 %0, %1, %2" : "=v"(r) : "v"(lo), "v"(hi)); return r; }
; __device__ __forceinline__ void lru_item(const Params& p, LAS unsigned char* L, int item, bool load_w) {
;     ...
;         if (cthr) {
;             if (pos >= 0) xr[r] = *(const u32x4*)(Z2 + (unsigned)((rbase + pos) * 3072u + chc));
;             else if (smp) {
;                 const float* hp = p.in[5] + ((size_t)b * 3 + (3 + pos)) * 1536 + chc;
;                 const f32x4 h0 = *(const f32x4*)hp, h1 = *(const f32x4*)(hp + 4);
;                 xr[r].x = cvt_pk_bf16(h0[0], h0[1]); xr[r].y = cvt_pk_bf16(h0[2], h0[3]); xr[r].z = cvt_pk_bf16(h1[0], h1[1]); xr[r].w = cvt_pk_bf16(h1[2], h1[3]);
;             }
.LBB0_1169:
	s_andn2_saveexec_b64 s[16:17], s[16:17]
	s_cbranch_execz .LBB0_1171
	v_readlane_b32 s48, v250, 4
	v_readlane_b32 s50, v250, 6
	v_readlane_b32 s51, v250, 7
	v_readlane_b32 s58, v250, 14
	v_readlane_b32 s59, v250, 15
	s_mul_i32 s26, s24, 0x1800
	s_mov_b64 s[50:51], s[58:59]
	s_mul_hi_u32 s23, s24, 0x1800
	s_add_u32 s26, s50, s26
	s_addc_u32 s27, s51, s23
	v_lshl_add_u64 v[4:5], v[60:61], 2, s[26:27]
	s_mov_b64 s[26:27], 0x1800
	v_add_co_u32_e32 v0, vcc, 0x1000, v4
	v_readlane_b32 s49, v250, 5
	s_nop 0
	v_addc_co_u32_e32 v1, vcc, 0, v5, vcc
	v_lshl_add_u64 v[4:5], v[4:5], 0, s[26:27]
	v_readlane_b32 s52, v250, 8
	v_readlane_b32 s53, v250, 9
	v_readlane_b32 s54, v250, 10
	v_readlane_b32 s55, v250, 11
	v_readlane_b32 s56, v250, 12
	v_readlane_b32 s57, v250, 13
	v_readlane_b32 s60, v250, 16
	v_readlane_b32 s61, v250, 17
	v_readlane_b32 s62, v250, 18
	v_readlane_b32 s63, v250, 19
	global_load_dwordx4 v[198:201], v[0:1], off offset:2048
	s_nop 0
	global_load_dwordx4 v[202:205], v[4:5], off offset:16

; __device__ __forceinline__ unsigned cvt_pk_bf16(float lo, float hi) { unsigned r; asm volatile("v_cvt_pk_bf16_f32 %0, %1, %2" : "=v"(r) : "v"(lo), "v"(hi)); return r; }
; __device__ __forceinline__ void lru_item(const Params& p, LAS unsigned char* L, int item, bool load_w) {
;     ...
;         if (cthr) {
;             if (pos >= 0) xr[r] = *(const u32x4*)(Z2 + (unsigned)((rbase + pos) * 3072u + chc));
;             else if (smp) {
;                 const float* hp = p.in[5] + ((size_t)b * 3 + (3 + pos)) * 1536 + chc;
;                 const f32x4 h0 = *(const f32x4*)hp, h1 = *(const f32x4*)(hp + 4);
;                 xr[r].x = cvt_pk_bf16(h0[0], h0[1]); xr[r].y = cvt_pk_bf16(h0[2], h0[3]); xr[r].z = cvt_pk_bf16(h1[0], h1[1]); xr[r].w = cvt_pk_bf16(h1[2], h1[3]);
;             }
.LBB0_1175:
	s_andn2_saveexec_b64 s[16:17], s[16:17]
	s_cbranch_execz .LBB0_1177
	v_readlane_b32 s48, v250, 4
	v_readlane_b32 s50, v250, 6
	v_readlane_b32 s51, v250, 7
	v_readlane_b32 s58, v250, 14
	v_readlane_b32 s59, v250, 15
	s_mul_i32 s26, s24, 0x1800
	s_mov_b64 s[50:51], s[58:59]
	s_mul_hi_u32 s23, s24, 0x1800
	s_add_u32 s26, s50, s26
	s_addc_u32 s27, s51, s23
	v_lshl_add_u64 v[4:5], v[60:61], 2, s[26:27]
	s_mov_b64 s[26:27], 0x3000
	v_add_co_u32_e32 v0, vcc, 0x3000, v4
	v_readlane_b32 s49, v250, 5
	s_nop 0
	v_addc_co_u32_e32 v1, vcc, 0, v5, vcc
	v_lshl_add_u64 v[4:5], v[4:5], 0, s[26:27]
	v_readlane_b32 s52, v250, 8
	v_readlane_b32 s53, v250, 9
	v_readlane_b32 s54, v250, 10
	v_readlane_b32 s55, v250, 11
	v_readlane_b32 s56, v250, 12
	v_readlane_b32 s57, v250, 13
	v_readlane_b32 s60, v250, 16
	v_readlane_b32 s61, v250, 17
	v_readlane_b32 s62, v250, 18
	v_readlane_b32 s63, v250, 19
	global_load_dwordx4 v[206:209], v[0:1], off
	s_nop 0
	global_load_dwordx4 v[210:213], v[4:5], off offset:16
	s_waitcnt vmcnt(0)
	v_cvt_pk_bf16_f32 v8, v190, v191
	v_cvt_pk_bf16_f32 v9, v192, v193
	v_cvt_pk_bf16_f32 v10, v194, v195
	v_cvt_pk_bf16_f32 v11, v196, v197
	v_cvt_pk_bf16_f32 v16, v198, v199
	v_cvt_pk_bf16_f32 v17, v200, v201
	v_cvt_pk_bf16_f32 v18, v202, v203
	v_cvt_pk_bf16_f32 v19, v204, v205
	v_cvt_pk_bf16_f32 v12, v206, v207
	v_cvt_pk_bf16_f32 v13, v208, v209
	v_cvt_pk_bf16_f32 v14, v210, v211
	v_cvt_pk_bf16_f32 v15, v212, v213

; __device__ __forceinline__ unsigned cvt_pk_bf16(float lo, float hi) { unsigned r; asm volatile("v_cvt_pk_bf16_f32 %0, %1, %2" : "=v"(r) : "v"(lo), "v"(hi)); return r; }
; __device__ __forceinline__ void lru_item(const Params& p, LAS unsigned char* L, int item, bool load_w) {
;     ...
;         if (cthr) {
;             if (pos >= 0) xr[r] = *(const u32x4*)(Z2 + (unsigned)((rbase + pos) * 3072u + chc));
;             else if (smp) {
;                 const float* hp = p.in[5] + ((size_t)b * 3 + (3 + pos)) * 1536 + chc;
;                 const f32x4 h0 = *(const f32x4*)hp, h1 = *(const f32x4*)(hp + 4);
;                 xr[r].x = cvt_pk_bf16(h0[0], h0[1]); xr[r].y = cvt_pk_bf16(h0[2], h0[3]); xr[r].z = cvt_pk_bf16(h1[0], h1[1]); xr[r].w = cvt_pk_bf16(h1[2], h1[3]);
;             }
.LBB0_1257:
	s_andn2_saveexec_b64 s[16:17], s[16:17]
	s_cbranch_execz .LBB0_1259
	v_readlane_b32 s48, v250, 4
	v_readlane_b32 s50, v250, 6
	v_readlane_b32 s51, v250, 7
	v_readlane_b32 s58, v250, 14
	v_readlane_b32 s59, v250, 15
	s_mul_i32 s26, s23, 0x1800
	s_mov_b64 s[50:51], s[58:59]
	s_mul_hi_u32 s25, s23, 0x1800
	s_add_u32 s26, s50, s26
	s_addc_u32 s27, s51, s25
	v_lshl_add_u64 v[10:11], v[60:61], 2, s[26:27]
	global_load_dwordx4 v[190:193], v[10:11], off
	global_load_dwordx4 v[194:197], v[10:11], off offset:16
	v_readlane_b32 s49, v250, 5
	v_readlane_b32 s52, v250, 8
	v_readlane_b32 s53, v250, 9
	v_readlane_b32 s54, v250, 10
	v_readlane_b32 s55, v250, 11
	v_readlane_b32 s56, v250, 12
	v_readlane_b32 s57, v250, 13
	v_readlane_b32 s60, v250, 16
	v_readlane_b32 s61, v250, 17
	v_readlane_b32 s62, v250, 18
	v_readlane_b32 s63, v250, 19

; __device__ __forceinline__ unsigned cvt_pk_bf16(float lo, float hi) { unsigned r; asm volatile("v_cvt_pk_bf16_f32 %0, %1, %2" : "=v"(r) : "v"(lo), "v"(hi)); return r; }
; __device__ __forceinline__ void lru_item(const Params& p, LAS unsigned char* L, int item, bool load_w) {
;     ...
;         if (cthr) {
;             if (pos >= 0) xr[r] = *(const u32x4*)(Z2 + (unsigned)((rbase + pos) * 3072u + chc));
;             else if (smp) {
;                 const float* hp = p.in[5] + ((size_t)b * 3 + (3 + pos)) * 1536 + chc;
;                 const f32x4 h0 = *(const f32x4*)hp, h1 = *(const f32x4*)(hp + 4);
;                 xr[r].x = cvt_pk_bf16(h0[0], h0[1]); xr[r].y = cvt_pk_bf16(h0[2], h0[3]); xr[r].z = cvt_pk_bf16(h1[0], h1[1]); xr[r].w = cvt_pk_bf16(h1[2], h1[3]);
;             }
.LBB0_1263:
	s_andn2_saveexec_b64 s[16:17], s[16:17]
	s_cbranch_execz .LBB0_1265
	v_readlane_b32 s48, v250, 4
	v_readlane_b32 s50, v250, 6
	v_readlane_b32 s51, v250, 7
	v_readlane_b32 s58, v250, 14
	v_readlane_b32 s59, v250, 15
	s_mul_i32 s26, s23, 0x1800
	s_mov_b64 s[50:51], s[58:59]
	s_mul_hi_u32 s25, s23, 0x1800
	s_add_u32 s26, s50, s26
	s_addc_u32 s27, s51, s25
	v_lshl_add_u64 v[4:5], v[60:61], 2, s[26:27]
	s_mov_b64 s[26:27], 0x1800
	v_add_co_u32_e32 v0, vcc, 0x1000, v4
	v_readlane_b32 s49, v250, 5
	s_nop 0
	v_addc_co_u32_e32 v1, vcc, 0, v5, vcc
	v_lshl_add_u64 v[4:5], v[4:5], 0, s[26:27]
	v_readlane_b32 s52, v250, 8
	v_readlane_b32 s53, v250, 9
	v_readlane_b32 s54, v250, 10
	v_readlane_b32 s55, v250, 11
	v_readlane_b32 s56, v250, 12
	v_readlane_b32 s57, v250, 13
	v_readlane_b32 s60, v250, 16
	v_readlane_b32 s61, v250, 17
	v_readlane_b32 s62, v250, 18
	v_readlane_b32 s63, v250, 19
	global_load_dwordx4 v[198:201], v[0:1], off offset:2048
	s_nop 0
	global_load_dwordx4 v[202:205], v[4:5], off offset:16

; __device__ __forceinline__ unsigned cvt_pk_bf16(float lo, float hi) { unsigned r; asm volatile("v_cvt_pk_bf16_f32 %0, %1, %2" : "=v"(r) : "v"(lo), "v"(hi)); return r; }
; __device__ __forceinline__ void lru_item(const Params& p, LAS unsigned char* L, int item, bool load_w) {
;     ...
;         if (cthr) {
;             if (pos >= 0) xr[r] = *(const u32x4*)(Z2 + (unsigned)((rbase + pos) * 3072u + chc));
;             else if (smp) {
;                 const float* hp = p.in[5] + ((size_t)b * 3 + (3 + pos)) * 1536 + chc;
;                 const f32x4 h0 = *(const f32x4*)hp, h1 = *(const f32x4*)(hp + 4);
;                 xr[r].x = cvt_pk_bf16(h0[0], h0[1]); xr[r].y = cvt_pk_bf16(h0[2], h0[3]); xr[r].z = cvt_pk_bf16(h1[0], h1[1]); xr[r].w = cvt_pk_bf16(h1[2], h1[3]);
;             }
.LBB0_1269:
	s_andn2_saveexec_b64 s[16:17], s[16:17]
	s_cbranch_execz .LBB0_1271
	v_readlane_b32 s48, v250, 4
	v_readlane_b32 s50, v250, 6
	v_readlane_b32 s51, v250, 7
	v_readlane_b32 s58, v250, 14
	v_readlane_b32 s59, v250, 15
	s_mul_i32 s26, s23, 0x1800
	s_mov_b64 s[50:51], s[58:59]
	s_mul_hi_u32 s25, s23, 0x1800
	s_add_u32 s26, s50, s26
	s_addc_u32 s27, s51, s25
	v_lshl_add_u64 v[4:5], v[60:61], 2, s[26:27]
	s_mov_b64 s[26:27], 0x3000
	v_add_co_u32_e32 v0, vcc, 0x3000, v4
	v_readlane_b32 s49, v250, 5
	s_nop 0
	v_addc_co_u32_e32 v1, vcc, 0, v5, vcc
	v_lshl_add_u64 v[4:5], v[4:5], 0, s[26:27]
	v_readlane_b32 s52, v250, 8
	v_readlane_b32 s53, v250, 9
	v_readlane_b32 s54, v250, 10
	v_readlane_b32 s55, v250, 11
	v_readlane_b32 s56, v250, 12
	v_readlane_b32 s57, v250, 13
	v_readlane_b32 s60, v250, 16
	v_readlane_b32 s61, v250, 17
	v_readlane_b32 s62, v250, 18
	v_readlane_b32 s63, v250, 19
	global_load_dwordx4 v[206:209], v[0:1], off
	s_nop 0
	global_load_dwordx4 v[210:213], v[4:5], off offset:16
	s_waitcnt vmcnt(0)
	v_cvt_pk_bf16_f32 v12, v190, v191
	v_cvt_pk_bf16_f32 v13, v192, v193
	v_cvt_pk_bf16_f32 v14, v194, v195
	v_cvt_pk_bf16_f32 v15, v196, v197
	v_cvt_pk_bf16_f32 v8, v198, v199
	v_cvt_pk_bf16_f32 v9, v200, v201
	v_cvt_pk_bf16_f32 v10, v202, v203
	v_cvt_pk_bf16_f32 v11, v204, v205
	v_cvt_pk_bf16_f32 v28, v206, v207
	v_cvt_pk_bf16_f32 v29, v208, v209
	v_cvt_pk_bf16_f32 v30, v210, v211
	v_cvt_pk_bf16_f32 v31, v212, v213
